# attention unit epilogue: O tile staged through the wave-private q_pe LDS image, 8 global_store_dwordx4 per lane instead of 64 global_store_short
# speedup vs baseline: 1.0081x; 1.0081x over previous
; DI unsigned pk2(float a, float b) { f32x2 v = {a, b}; bfv2 r = __builtin_convertvector(v, bfv2); return __builtin_bit_cast(unsigned, r); }
; DI int crow(int r, int hi) { return (r & 3) + 8 * (r >> 2) + 4 * hi; }
; DI void attn_unit(const bf16_t* __restrict__ Qb, const bf16_t* __restrict__ Kh, const bf16_t* __restrict__ Vh, const bf16_t* __restrict__ Ph,
;                   bf16_t* __restrict__ Ob, int seq, float* __restrict__ lse_out, char* lds) {
;     ...
;   if (hi == 0) li_l[r32] = l_reg; asm volatile("s_waitcnt lgkmcnt(0)" ::: "memory");
;   if (lse_out != nullptr && hi == 0) lse_out[wid * 32 + r32] = m_reg + __builtin_amdgcn_logf(l_reg);
;   float rli[16];
; #pragma unroll
;   for (int r = 0; r < 16; ++r) rli[r] = __builtin_amdgcn_rcpf(li_l[crow(r, hi)]);
;   bf16_t* Ow = Ob + (long)(wid * 32) * LDO;
; #pragma unroll
;   for (int r = 0; r < 16; ++r) { const int orow = crow(r, hi);
; #pragma unroll
;     for (int d0 = 0; d0 < 4; ++d0) { const float v = o[d0][r] * rli[r]; Ow[(long)orow * LDO + d0 * 32 + r32] = (bf16_t)(pk2(v, v) & 0xffffu); } }
.LBB0_649:
	s_or_b64 exec, exec, s[2:3]
	v_add_u32_e32 v74, v137, v134
	ds_read_b128 v[66:69], v74
	ds_read_b128 v[70:73], v74 offset:32
	ds_read_b128 v[76:79], v74 offset:64
	ds_read_b128 v[80:83], v74 offset:96
	s_lshl_b64 s[2:3], s[34:35], 11
	s_add_u32 s2, s93, s2
	s_addc_u32 s3, s94, s3
	s_cmp_eq_u64 s[28:29], 0
	v_ashrrev_i32_e32 v137, 31, v136
	s_cselect_b32 s3, s3, s29
	s_cselect_b32 s2, s2, s28
	v_lshlrev_b32_e32 v134, 1, v159
	v_mul_u32_u24_e32 v84, 14, v159
	v_sub_u32_e32 v84, v163, v84
	v_lshl_add_u32 v84, v160, 9, v84
	v_lshrrev_b32_e32 v85, 4, v159
	v_lshl_add_u32 v85, v160, 1, v85
	v_add_u32_e32 v85, v136, v85
	v_and_b32_e32 v90, 15, v159
	v_lshlrev_b32_e32 v90, 4, v90
	v_lshl_add_u32 v85, v85, 11, v90
	v_add_u32_e32 v90, 0x2000, v85
	v_add_u32_e32 v91, 0x4000, v85
	v_add_u32_e32 v92, 0x6000, v85
	s_waitcnt lgkmcnt(0)
	v_rcp_f32_e32 v66, v66
	v_rcp_f32_e32 v67, v67
	v_rcp_f32_e32 v68, v68
	v_rcp_f32_e32 v69, v69
	v_rcp_f32_e32 v70, v70
	v_rcp_f32_e32 v71, v71
	v_rcp_f32_e32 v72, v72
	v_rcp_f32_e32 v73, v73
	v_rcp_f32_e32 v76, v76
	v_rcp_f32_e32 v77, v77
	v_rcp_f32_e32 v78, v78
	v_rcp_f32_e32 v79, v79
	v_rcp_f32_e32 v80, v80
	v_rcp_f32_e32 v81, v81
	v_rcp_f32_e32 v82, v82
	v_rcp_f32_e32 v83, v83
	v_mul_f32_e32 v86, v2, v66
	v_mul_f32_e32 v87, v50, v66
	v_mul_f32_e32 v88, v34, v66
	v_mul_f32_e32 v89, v18, v66
	v_cvt_pk_bf16_f32 v86, v86, v86
	v_cvt_pk_bf16_f32 v87, v87, v87
	v_cvt_pk_bf16_f32 v88, v88, v88
	v_cvt_pk_bf16_f32 v89, v89, v89
	ds_write_b16 v84, v86
	ds_write_b16 v84, v87 offset:64
	ds_write_b16 v84, v88 offset:128
	ds_write_b16 v84, v89 offset:192
	v_mul_f32_e32 v86, v3, v67
	v_mul_f32_e32 v87, v51, v67
	v_mul_f32_e32 v88, v35, v67
	v_mul_f32_e32 v89, v19, v67
	v_cvt_pk_bf16_f32 v86, v86, v86
	v_cvt_pk_bf16_f32 v87, v87, v87
	v_cvt_pk_bf16_f32 v88, v88, v88
	v_cvt_pk_bf16_f32 v89, v89, v89
	ds_write_b16 v84, v86 offset:256
	ds_write_b16 v84, v87 offset:320
	ds_write_b16 v84, v88 offset:384
	ds_write_b16 v84, v89 offset:448
	v_mul_f32_e32 v86, v4, v68
	v_mul_f32_e32 v87, v52, v68
	v_mul_f32_e32 v88, v36, v68
	v_mul_f32_e32 v89, v20, v68
	v_cvt_pk_bf16_f32 v86, v86, v86
	v_cvt_pk_bf16_f32 v87, v87, v87
	v_cvt_pk_bf16_f32 v88, v88, v88
	v_cvt_pk_bf16_f32 v89, v89, v89
	ds_write_b16 v84, v86 offset:512
	ds_write_b16 v84, v87 offset:576
	ds_write_b16 v84, v88 offset:640
	ds_write_b16 v84, v89 offset:704
	v_mul_f32_e32 v86, v5, v69
	v_mul_f32_e32 v87, v53, v69
	v_mul_f32_e32 v88, v37, v69
	v_mul_f32_e32 v89, v21, v69
	v_cvt_pk_bf16_f32 v86, v86, v86
	v_cvt_pk_bf16_f32 v87, v87, v87
	v_cvt_pk_bf16_f32 v88, v88, v88
	v_cvt_pk_bf16_f32 v89, v89, v89
	ds_write_b16 v84, v86 offset:768
	ds_write_b16 v84, v87 offset:832
	ds_write_b16 v84, v88 offset:896
	ds_write_b16 v84, v89 offset:960
	v_mul_f32_e32 v86, v6, v70
	v_mul_f32_e32 v87, v54, v70
	v_mul_f32_e32 v88, v38, v70
	v_mul_f32_e32 v89, v22, v70
	v_cvt_pk_bf16_f32 v86, v86, v86
	v_cvt_pk_bf16_f32 v87, v87, v87
	v_cvt_pk_bf16_f32 v88, v88, v88
	v_cvt_pk_bf16_f32 v89, v89, v89
	ds_write_b16 v84, v86 offset:2048
	ds_write_b16 v84, v87 offset:2112
	ds_write_b16 v84, v88 offset:2176
	ds_write_b16 v84, v89 offset:2240
	v_mul_f32_e32 v86, v7, v71
	v_mul_f32_e32 v87, v55, v71
	v_mul_f32_e32 v88, v39, v71
	v_mul_f32_e32 v89, v23, v71
	v_cvt_pk_bf16_f32 v86, v86, v86
	v_cvt_pk_bf16_f32 v87, v87, v87
	v_cvt_pk_bf16_f32 v88, v88, v88
	v_cvt_pk_bf16_f32 v89, v89, v89
	ds_write_b16 v84, v86 offset:2304
	ds_write_b16 v84, v87 offset:2368
	ds_write_b16 v84, v88 offset:2432
	ds_write_b16 v84, v89 offset:2496
	v_mul_f32_e32 v86, v8, v72
	v_mul_f32_e32 v87, v56, v72
	v_mul_f32_e32 v88, v40, v72
	v_mul_f32_e32 v89, v24, v72
	v_cvt_pk_bf16_f32 v86, v86, v86
	v_cvt_pk_bf16_f32 v87, v87, v87
	v_cvt_pk_bf16_f32 v88, v88, v88
	v_cvt_pk_bf16_f32 v89, v89, v89
	ds_write_b16 v84, v86 offset:2560
	ds_write_b16 v84, v87 offset:2624
	ds_write_b16 v84, v88 offset:2688
	ds_write_b16 v84, v89 offset:2752
	v_mul_f32_e32 v86, v9, v73
	v_mul_f32_e32 v87, v57, v73
	v_mul_f32_e32 v88, v41, v73
	v_mul_f32_e32 v89, v25, v73
	v_cvt_pk_bf16_f32 v86, v86, v86
	v_cvt_pk_bf16_f32 v87, v87, v87
	v_cvt_pk_bf16_f32 v88, v88, v88
	v_cvt_pk_bf16_f32 v89, v89, v89
	ds_write_b16 v84, v86 offset:2816
	ds_write_b16 v84, v87 offset:2880
	ds_write_b16 v84, v88 offset:2944
	ds_write_b16 v84, v89 offset:3008
	s_waitcnt lgkmcnt(0)
; DI unsigned pk2(float a, float b) { f32x2 v = {a, b}; bfv2 r = __builtin_convertvector(v, bfv2); return __builtin_bit_cast(unsigned, r); }
; DI int crow(int r, int hi) { return (r & 3) + 8 * (r >> 2) + 4 * hi; }
; DI void attn_unit(const bf16_t* __restrict__ Qb, const bf16_t* __restrict__ Kh, const bf16_t* __restrict__ Vh, const bf16_t* __restrict__ Ph,
;                   bf16_t* __restrict__ Ob, int seq, float* __restrict__ lse_out, char* lds) {
;     ...
;   float rli[16];
; #pragma unroll
;   for (int r = 0; r < 16; ++r) rli[r] = __builtin_amdgcn_rcpf(li_l[crow(r, hi)]);
;   bf16_t* Ow = Ob + (long)(wid * 32) * LDO;
; #pragma unroll
;   for (int r = 0; r < 16; ++r) { const int orow = crow(r, hi);
; #pragma unroll
;     for (int d0 = 0; d0 < 4; ++d0) { const float v = o[d0][r] * rli[r]; Ow[(long)orow * LDO + d0 * 32 + r32] = (bf16_t)(pk2(v, v) & 0xffffu); } }
	ds_read_b128 v[2:5], v163
	ds_read_b128 v[6:9], v163 offset:1024
	ds_read_b128 v[50:53], v163 offset:2048
	ds_read_b128 v[54:57], v163 offset:3072
	s_waitcnt lgkmcnt(0)
	global_store_dwordx4 v85, v[2:5], s[2:3]
	global_store_dwordx4 v90, v[6:9], s[2:3]
	global_store_dwordx4 v91, v[50:53], s[2:3]
	global_store_dwordx4 v92, v[54:57], s[2:3]
	v_add_u32_e32 v85, 0x8000, v85
	v_add_u32_e32 v90, 0x8000, v90
	v_add_u32_e32 v91, 0x8000, v91
	v_add_u32_e32 v92, 0x8000, v92
	v_mul_f32_e32 v86, v10, v76
	v_mul_f32_e32 v87, v58, v76
	v_mul_f32_e32 v88, v42, v76
	v_mul_f32_e32 v89, v26, v76
	v_cvt_pk_bf16_f32 v86, v86, v86
	v_cvt_pk_bf16_f32 v87, v87, v87
	v_cvt_pk_bf16_f32 v88, v88, v88
	v_cvt_pk_bf16_f32 v89, v89, v89
	ds_write_b16 v84, v86
	ds_write_b16 v84, v87 offset:64
	ds_write_b16 v84, v88 offset:128
	ds_write_b16 v84, v89 offset:192
	v_mul_f32_e32 v86, v11, v77
	v_mul_f32_e32 v87, v59, v77
	v_mul_f32_e32 v88, v43, v77
	v_mul_f32_e32 v89, v27, v77
	v_cvt_pk_bf16_f32 v86, v86, v86
	v_cvt_pk_bf16_f32 v87, v87, v87
	v_cvt_pk_bf16_f32 v88, v88, v88
	v_cvt_pk_bf16_f32 v89, v89, v89
	ds_write_b16 v84, v86 offset:256
	ds_write_b16 v84, v87 offset:320
	ds_write_b16 v84, v88 offset:384
	ds_write_b16 v84, v89 offset:448
	v_mul_f32_e32 v86, v12, v78
	v_mul_f32_e32 v87, v60, v78
	v_mul_f32_e32 v88, v44, v78
	v_mul_f32_e32 v89, v28, v78
	v_cvt_pk_bf16_f32 v86, v86, v86
	v_cvt_pk_bf16_f32 v87, v87, v87
	v_cvt_pk_bf16_f32 v88, v88, v88
	v_cvt_pk_bf16_f32 v89, v89, v89
	ds_write_b16 v84, v86 offset:512
	ds_write_b16 v84, v87 offset:576
	ds_write_b16 v84, v88 offset:640
	ds_write_b16 v84, v89 offset:704
	v_mul_f32_e32 v86, v13, v79
	v_mul_f32_e32 v87, v61, v79
	v_mul_f32_e32 v88, v45, v79
	v_mul_f32_e32 v89, v29, v79
	v_cvt_pk_bf16_f32 v86, v86, v86
	v_cvt_pk_bf16_f32 v87, v87, v87
	v_cvt_pk_bf16_f32 v88, v88, v88
	v_cvt_pk_bf16_f32 v89, v89, v89
	ds_write_b16 v84, v86 offset:768
	ds_write_b16 v84, v87 offset:832
	ds_write_b16 v84, v88 offset:896
	ds_write_b16 v84, v89 offset:960
	v_mul_f32_e32 v86, v14, v80
	v_mul_f32_e32 v87, v62, v80
	v_mul_f32_e32 v88, v46, v80
	v_mul_f32_e32 v89, v30, v80
	v_cvt_pk_bf16_f32 v86, v86, v86
	v_cvt_pk_bf16_f32 v87, v87, v87
	v_cvt_pk_bf16_f32 v88, v88, v88
	v_cvt_pk_bf16_f32 v89, v89, v89
	ds_write_b16 v84, v86 offset:2048
	ds_write_b16 v84, v87 offset:2112
	ds_write_b16 v84, v88 offset:2176
	ds_write_b16 v84, v89 offset:2240
	v_mul_f32_e32 v86, v15, v81
	v_mul_f32_e32 v87, v63, v81
	v_mul_f32_e32 v88, v47, v81
	v_mul_f32_e32 v89, v31, v81
	v_cvt_pk_bf16_f32 v86, v86, v86
	v_cvt_pk_bf16_f32 v87, v87, v87
	v_cvt_pk_bf16_f32 v88, v88, v88
	v_cvt_pk_bf16_f32 v89, v89, v89
	ds_write_b16 v84, v86 offset:2304
	ds_write_b16 v84, v87 offset:2368
	ds_write_b16 v84, v88 offset:2432
	ds_write_b16 v84, v89 offset:2496
	v_mul_f32_e32 v86, v16, v82
	v_mul_f32_e32 v87, v64, v82
	v_mul_f32_e32 v88, v48, v82
	v_mul_f32_e32 v89, v32, v82
	v_cvt_pk_bf16_f32 v86, v86, v86
	v_cvt_pk_bf16_f32 v87, v87, v87
	v_cvt_pk_bf16_f32 v88, v88, v88
	v_cvt_pk_bf16_f32 v89, v89, v89
	ds_write_b16 v84, v86 offset:2560
	ds_write_b16 v84, v87 offset:2624
	ds_write_b16 v84, v88 offset:2688
	ds_write_b16 v84, v89 offset:2752
	v_mul_f32_e32 v86, v17, v83
	v_mul_f32_e32 v87, v65, v83
	v_mul_f32_e32 v88, v49, v83
	v_mul_f32_e32 v89, v33, v83
	v_cvt_pk_bf16_f32 v86, v86, v86
	v_cvt_pk_bf16_f32 v87, v87, v87
	v_cvt_pk_bf16_f32 v88, v88, v88
	v_cvt_pk_bf16_f32 v89, v89, v89
	ds_write_b16 v84, v86 offset:2816
	ds_write_b16 v84, v87 offset:2880
	ds_write_b16 v84, v88 offset:2944
	ds_write_b16 v84, v89 offset:3008
	s_waitcnt lgkmcnt(0)
	ds_read_b128 v[34:37], v163
	ds_read_b128 v[38:41], v163 offset:1024
	ds_read_b128 v[18:21], v163 offset:2048
	ds_read_b128 v[22:25], v163 offset:3072
	s_waitcnt lgkmcnt(0)
	global_store_dwordx4 v85, v[34:37], s[2:3]
	global_store_dwordx4 v90, v[38:41], s[2:3]
	global_store_dwordx4 v91, v[18:21], s[2:3]
	global_store_dwordx4 v92, v[22:25], s[2:3]
	s_nop 0
	s_mov_b64 s[2:3], 0
